# XCD-aware item mapping in inproj / merge / outproj now guarded: used only when all 8 XCDs are populated (barrier set-up word), otherwise the flat queue / static mapping; inproj single code path with r
# baseline (speedup 1.0000x reference)
; template <int MB, bool PF2 = true>
; DI void gemm_main(const u16* __restrict__ A, int lda, const u16* __restrict__ B, int ldb, int K, f32x16 (&acc)[MB][2], GemmLds* s, int tid) {
;   const int lane = tid & 63, w = tid >> 6, r = lane & 31, h = lane >> 5, wm = w >> 1, wn = w & 1;
;   const int srow = tid >> 3, skc = (tid & 7) * 8;
;   const unsigned oa0 = (unsigned)(srow * lda + skc) * 2u, oa1 = oa0 + 64u * lda, oa2 = oa0 + 128u * lda, oa3 = oa0 + 192u * lda;
;   const unsigned ob0 = (unsigned)(srow * ldb + skc) * 2u, ob1 = ob0 + 64u * ldb, ob2 = ob0 + 128u * ldb, ob3 = ob0 + 192u * ldb;
; DI void phase_inproj(const Params& p, int l, char* smem, int tid) {
;     ...
;   for (int it = blockIdx.x; it < 272 * 24; it += gridDim.x) {
;     const int mt = it / 24, nt = it % 24, m0 = mt * 128, n0 = nt * 128;
;     f32x16 acc[2][2]; zero_acc<2>(acc);
;     gemm_main<2>(p.xn + (size_t)m0 * 1024, 1024, Wt + (size_t)n0 * 1024, 1024, 1024, acc, s, tid);
.LBB0_515:
	v_readlane_b32 s0, v253, 14
	v_readlane_b32 s1, v253, 15
	v_mov_b32_e32 v0, v206
	s_andn2_b64 vcc, exec, s[0:1]
	s_cbranch_vccnz .LBB0_550
	v_readlane_b32 s0, v254, 19
	v_and_b32_e32 v113, 63, v206
	v_lshrrev_b32_e32 v114, 6, v206
	v_lshrrev_b32_e32 v115, 3, v113
	v_lshl_add_u32 v115, v114, 5, v115
	v_lshlrev_b32_e32 v115, 11, v115
	v_and_b32_e32 v116, 7, v113
	v_lshrrev_b32_e32 v113, 4, v113
	v_xor_b32_e32 v116, v116, v113
	v_lshl_or_b32 v98, v116, 4, v115
	v_xor_b32_e32 v99, 64, v98
	v_add_u32_e32 v99, 16384, v99
	v_add_u32_e32 v100, 32768, v98
	v_add_u32_e32 v101, 32768, v99
	v_lshrrev_b32_e32 v117, 6, v206
	v_and_b32_e32 v113, 31, v206
	v_bfe_u32 v114, v206, 5, 1
	v_bfe_u32 v115, v113, 1, 3
	v_xor_b32_e32 v115, v115, v114
	v_lshlrev_b32_e32 v115, 4, v115
	v_lshl_or_b32 v115, v113, 7, v115
	v_lshrrev_b32_e32 v116, 7, v206
	v_lshl_add_u32 v102, v116, 13, v115
	v_bfe_u32 v116, v206, 6, 1
	v_lshl_add_u32 v106, v116, 13, v115
	v_add_u32_e32 v106, 0x4000, v106
	v_xor_b32_e32 v103, 32, v102
	v_xor_b32_e32 v107, 32, v106
	v_xor_b32_e32 v104, 64, v102
	v_xor_b32_e32 v108, 64, v106
	v_xor_b32_e32 v105, 96, v102
	v_xor_b32_e32 v109, 96, v106
	v_and_b32_e32 v113, 31, v206
	v_lshrrev_b32_e32 v114, 7, v206
	v_lshl_add_u32 v113, v114, 6, v113
	v_bfe_u32 v115, v206, 5, 1
	v_lshlrev_b32_e32 v116, 3, v115
	v_mul_u32_u24_e32 v110, 0xe00, v113
	v_add_u32_e32 v110, v110, v116
	v_mul_u32_u24_e32 v111, 0x640, v113
	v_add_u32_e32 v111, v111, v116
	v_mul_u32_u24_e32 v116, 0x8800, v115
	v_lshl_add_u32 v112, v113, 1, v116
	v_lshrrev_b32_e32 v113, 6, v206
	v_mul_u32_u24_e32 v113, 0x2400, v113
	v_add_u32_e32 v113, 0x8000, v113
	v_and_b32_e32 v114, 31, v206
	v_mul_u32_u24_e32 v114, 0x90, v114
	v_bfe_u32 v115, v206, 5, 1
	v_lshl_add_u32 v114, v115, 3, v114
	v_add_u32_e32 v118, v113, v114
	v_bfe_u32 v114, v206, 3, 3
	v_mul_u32_u24_e32 v114, 0x90, v114
	v_and_b32_e32 v115, 7, v206
	v_lshl_add_u32 v114, v115, 4, v114
	v_add_u32_e32 v119, v113, v114
	v_bfe_u32 v113, v206, 3, 3
	v_lshrrev_b32_e32 v114, 7, v206
	v_lshl_add_u32 v113, v114, 6, v113
	v_mul_u32_u24_e32 v113, 0xe00, v113
	v_bfe_u32 v114, v206, 6, 1
	v_lshlrev_b32_e32 v114, 7, v114
	v_and_b32_e32 v115, 7, v206
	v_lshl_or_b32 v114, v115, 4, v114
	v_add_u32_e32 v120, v113, v114
	v_bfe_u32 v113, v206, 3, 3
	v_lshrrev_b32_e32 v114, 7, v206
	v_lshl_add_u32 v113, v114, 6, v113
	v_mul_u32_u24_e32 v113, 0x640, v113
	v_bfe_u32 v114, v206, 6, 1
	v_lshlrev_b32_e32 v114, 7, v114
	v_and_b32_e32 v115, 7, v206
	v_lshl_or_b32 v114, v115, 4, v114
	v_add_u32_e32 v121, v113, v114
	v_readfirstlane_b32 s10, v117
	s_lshl_b32 s10, s10, 12
	s_mul_i32 s1, s0, 0x600000
	s_add_u32 s14, s96, 0x1ab20000
	s_addc_u32 s15, s97, 0
	s_add_u32 s14, s14, s1
	s_addc_u32 s15, s15, 0
	v_readlane_b32 s0, v254, 19
	s_getreg_b32 s16, hwreg(HW_REG_XCC_ID, 0, 4)
	v_mov_b32_e32 v116, 0x125f0
	ds_read_b32 v114, v116 offset:16
	ds_read_b32 v113, v116 offset:20
	s_waitcnt lgkmcnt(0)
	v_readfirstlane_b32 s2, v113
	s_mov_b32 s12, s48
	s_mov_b32 s17, s49
	s_cmp_eq_u32 s2, 8
	s_cbranch_scc0 .Lipx_flat
	s_cmp_eq_u32 s10, 0
	s_cbranch_scc0 .Lipx_wait
	s_mov_b64 s[6:7], exec
	s_mov_b64 exec, 1
	s_lshl_b32 s8, s16, 8
	s_lshl_b32 s9, s0, 11
	s_add_u32 s8, s8, s9
	s_add_u32 s8, s8, 0x1da60000
	s_add_u32 s8, s96, s8
	s_addc_u32 s9, s97, 0
	v_mov_b32_e32 v113, 1
	v_mov_b32_e32 v115, 0
	global_atomic_add v115, v115, v113, s[8:9] sc0
	s_waitcnt vmcnt(0)
	ds_write_b32 v116, v115
	s_waitcnt lgkmcnt(0)
	s_mov_b64 exec, s[6:7]
.Lipx_wait:
	s_barrier
	ds_read_b32 v115, v116
	s_waitcnt lgkmcnt(0)
	v_readfirstlane_b32 s12, v115
	v_readfirstlane_b32 s17, v114
	s_lshr_b32 s2, s16, 2
	s_lshl_b32 s2, s2, 10
	s_or_b32 s17, s17, s2
	s_and_b32 s2, s16, 3
	s_mul_i32 s2, s2, 6
	s_lshl_b32 s2, s2, 18
	s_or_b32 s17, s17, s2
	s_bitset1_b32 s17, 31
.Lipx_flat:
	s_movk_i32 s2, 0x1980
	s_bitcmp1_b32 s17, 31
	s_cselect_b32 s2, 0x330, s2
	s_cmp_lt_u32 s12, s2
	s_cbranch_scc0 .Lip_done
	s_mul_hi_u32 s0, s12, 0xaaaaaaab
	s_bitcmp1_b32 s17, 31
	s_cselect_b32 s2, 2, 4
	s_lshr_b32 s0, s0, s2
	s_bitcmp1_b32 s17, 31
	s_cselect_b32 s2, 6, 24
	s_mul_i32 s2, s0, s2
	s_sub_u32 s1, s12, s2
	s_bfe_u32 s2, s17, 0x80012
	s_add_u32 s1, s1, s2
	s_bitcmp1_b32 s17, 31
	s_cselect_b32 s2, 1, 0
	s_lshl_b32 s0, s0, s2
	s_bfe_u32 s2, s17, 0x8000a
	s_add_u32 s0, s0, s2
	s_lshl_b32 s2, s0, 18
	s_add_u32 s4, s96, s2
	s_addc_u32 s5, s97, 0
	s_lshl_b32 s2, s1, 18
	s_add_u32 s8, s14, s2
	s_addc_u32 s9, s15, 0
	s_add_u32 m0, s10, 0x0
	s_nop 0
	global_load_lds_dwordx4 v98, s[4:5]
	s_add_u32 m0, s10, 0x400
	s_nop 0
	global_load_lds_dwordx4 v99, s[4:5]
	s_add_u32 m0, s10, 0x800
	s_nop 0
	global_load_lds_dwordx4 v100, s[4:5]
	s_add_u32 m0, s10, 0xc00
	s_nop 0
	global_load_lds_dwordx4 v101, s[4:5]
	s_add_u32 m0, s10, 0x4000
	s_nop 0
	global_load_lds_dwordx4 v98, s[8:9]
	s_add_u32 m0, s10, 0x4400
	s_nop 0
	global_load_lds_dwordx4 v99, s[8:9]
	s_add_u32 m0, s10, 0x4800
	s_nop 0
	global_load_lds_dwordx4 v100, s[8:9]
	s_add_u32 m0, s10, 0x4c00
	s_nop 0
	global_load_lds_dwordx4 v101, s[8:9]
	s_add_u32 s4, s4, 128
	s_addc_u32 s5, s5, 0
	s_add_u32 s8, s8, 128
	s_addc_u32 s9, s9, 0
.Lip_item:
	s_mul_hi_u32 s0, s12, 0xaaaaaaab
	s_bitcmp1_b32 s17, 31
	s_cselect_b32 s2, 2, 4
	s_lshr_b32 s0, s0, s2
	s_bitcmp1_b32 s17, 31
	s_cselect_b32 s2, 6, 24
	s_mul_i32 s2, s0, s2
	s_sub_u32 s1, s12, s2
	s_bfe_u32 s2, s17, 0x80012
	s_add_u32 s1, s1, s2
	s_bitcmp1_b32 s17, 31
	s_cselect_b32 s2, 1, 0
	s_lshl_b32 s0, s0, s2
	s_bfe_u32 s2, s17, 0x8000a
	s_add_u32 s0, s0, s2
	s_mov_b32 s94, 0

; #define G_STORE(S, bf) { *(uint4*)&s->a[bf][srow][skc] = S##a0; *(uint4*)&s->a[bf][srow + 32][skc] = S##a1; \
;     if (MB == 2) { *(uint4*)&s->a[bf][srow + 64][skc] = S##a2; *(uint4*)&s->a[bf][srow + 96][skc] = S##a3; } \
;     *(uint4*)&s->b[bf][srow][skc] = S##b0; *(uint4*)&s->b[bf][srow + 32][skc] = S##b1; *(uint4*)&s->b[bf][srow + 64][skc] = S##b2; *(uint4*)&s->b[bf][srow + 96][skc] = S##b3; }
; template <int MB, bool PF2 = true>
; DI void gemm_main(const u16* __restrict__ A, int lda, const u16* __restrict__ B, int ldb, int K, f32x16 (&acc)[MB][2], GemmLds* s, int tid) {
;     ...
;   for (int kt = 0; kt < KT; kt += 2) {
;     { const int k2 = min((kt + 2) * 64, klast); G_LOAD(q, k2); }
;     __builtin_amdgcn_sched_barrier(0);
;     G_COMPUTE(0);
;     G_STORE(p, 1);
;     __syncthreads();
;     { const int k3 = min((kt + 3) * 64, klast); G_LOAD(p, k3); }
;     __builtin_amdgcn_sched_barrier(0);
;     G_COMPUTE(1);
;     G_STORE(q, 0);
;     __syncthreads();
; DI void phase_inproj(const Params& p, int l, char* smem, int tid) {
;     ...
;   for (int it = blockIdx.x; it < 272 * 24; it += gridDim.x) {
;     const int mt = it / 24, nt = it % 24, m0 = mt * 128, n0 = nt * 128;
;     f32x16 acc[2][2]; zero_acc<2>(acc);
;     gemm_main<2>(p.xn + (size_t)m0 * 1024, 1024, Wt + (size_t)n0 * 1024, 1024, 1024, acc, s, tid);
.Lip_last:
	s_and_b32 s6, s17, 0x3ff
	s_add_u32 s6, s12, s6
	s_movk_i32 s2, 0x1980
	s_bitcmp1_b32 s17, 31
	s_cselect_b32 s2, 0x330, s2
	s_cmp_lt_u32 s6, s2
	s_cbranch_scc0 .Lip_nopf
	s_mul_hi_u32 s2, s6, 0xaaaaaaab
	s_bitcmp1_b32 s17, 31
	s_cselect_b32 s4, 2, 4
	s_lshr_b32 s2, s2, s4
	s_bitcmp1_b32 s17, 31
	s_cselect_b32 s4, 6, 24
	s_mul_i32 s4, s2, s4
	s_sub_u32 s3, s6, s4
	s_bfe_u32 s4, s17, 0x80012
	s_add_u32 s3, s3, s4
	s_bitcmp1_b32 s17, 31
	s_cselect_b32 s4, 1, 0
	s_lshl_b32 s2, s2, s4
	s_bfe_u32 s4, s17, 0x8000a
	s_add_u32 s2, s2, s4
	s_lshl_b32 s2, s2, 18
	s_add_u32 s4, s96, s2
	s_addc_u32 s5, s97, 0
	s_lshl_b32 s3, s3, 18
	s_add_u32 s8, s14, s3
	s_addc_u32 s9, s15, 0
	ds_read_b128 v[82:85], v103 offset:32768
	ds_read_b128 v[90:93], v107 offset:32768
	ds_read_b128 v[86:89], v103 offset:36864
	ds_read_b128 v[94:97], v107 offset:36864
	s_waitcnt lgkmcnt(4)
	s_add_u32 m0, s10, 0x0
	v_mfma_f32_32x32x16_bf16 v[2:17], v[74:77], v[66:69], v[2:17]
	global_load_lds_dwordx4 v98, s[4:5]
	s_add_u32 m0, s10, 0x400
	v_mfma_f32_32x32x16_bf16 v[18:33], v[78:81], v[66:69], v[18:33]
	global_load_lds_dwordx4 v99, s[4:5]
	s_add_u32 m0, s10, 0x800
	v_mfma_f32_32x32x16_bf16 v[34:49], v[74:77], v[70:73], v[34:49]
	global_load_lds_dwordx4 v100, s[4:5]
	s_add_u32 m0, s10, 0xc00
	v_mfma_f32_32x32x16_bf16 v[50:65], v[78:81], v[70:73], v[50:65]
	global_load_lds_dwordx4 v101, s[4:5]
	s_add_u32 s4, s4, 128
	s_addc_u32 s5, s5, 0
	ds_read_b128 v[66:69], v104 offset:32768
	ds_read_b128 v[74:77], v108 offset:32768
	ds_read_b128 v[70:73], v104 offset:36864
	ds_read_b128 v[78:81], v108 offset:36864
	s_waitcnt lgkmcnt(4)
	s_add_u32 m0, s10, 0x4000
	v_mfma_f32_32x32x16_bf16 v[2:17], v[90:93], v[82:85], v[2:17]
	global_load_lds_dwordx4 v98, s[8:9]
	s_add_u32 m0, s10, 0x4400
	v_mfma_f32_32x32x16_bf16 v[18:33], v[94:97], v[82:85], v[18:33]
	global_load_lds_dwordx4 v99, s[8:9]
	s_add_u32 m0, s10, 0x4800
	v_mfma_f32_32x32x16_bf16 v[34:49], v[90:93], v[86:89], v[34:49]
	global_load_lds_dwordx4 v100, s[8:9]
	s_add_u32 m0, s10, 0x4c00
	v_mfma_f32_32x32x16_bf16 v[50:65], v[94:97], v[86:89], v[50:65]
	global_load_lds_dwordx4 v101, s[8:9]
	s_add_u32 s8, s8, 128
	s_addc_u32 s9, s9, 0
	ds_read_b128 v[82:85], v105 offset:32768
	ds_read_b128 v[90:93], v109 offset:32768
	ds_read_b128 v[86:89], v105 offset:36864
	ds_read_b128 v[94:97], v109 offset:36864
	s_waitcnt lgkmcnt(4)
	v_mfma_f32_32x32x16_bf16 v[2:17], v[74:77], v[66:69], v[2:17]
	v_mfma_f32_32x32x16_bf16 v[18:33], v[78:81], v[66:69], v[18:33]
	v_mfma_f32_32x32x16_bf16 v[34:49], v[74:77], v[70:73], v[34:49]
	v_mfma_f32_32x32x16_bf16 v[50:65], v[78:81], v[70:73], v[50:65]
	s_waitcnt lgkmcnt(0)
	s_barrier
	v_mfma_f32_32x32x16_bf16 v[2:17], v[90:93], v[82:85], v[2:17]
	v_mfma_f32_32x32x16_bf16 v[18:33], v[94:97], v[82:85], v[18:33]
	v_mfma_f32_32x32x16_bf16 v[34:49], v[90:93], v[86:89], v[34:49]
	v_mfma_f32_32x32x16_bf16 v[50:65], v[94:97], v[86:89], v[50:65]
	s_branch .Lip_kdone

; DI void phase_inproj(const Params& p, int l, char* smem, int tid) {
;     ...
;   for (int it = blockIdx.x; it < 272 * 24; it += gridDim.x) {
.Lip_e1_end:
.Lip_epi_done:
	s_and_b32 s2, s17, 0x3ff
	s_add_u32 s12, s12, s2
	s_movk_i32 s2, 0x1980
	s_bitcmp1_b32 s17, 31
	s_cselect_b32 s2, 0x330, s2
	s_cmp_lt_u32 s12, s2
	s_cbranch_scc1 .Lip_item

; DI void phase_merge(const Params& p, int l, char* smem, int tid) {
;     ...
;   for (int it = (dyn ? fetch_item(qc, smem) : (int)blockIdx.x); it < 544 * 8; it = (dyn ? fetch_item(qc, smem) : it + (int)gridDim.x)) {
.Lmg_item:
	v_mov_b32_e32 v153, 0x12604
	ds_read_b32 v151, v153
	s_waitcnt lgkmcnt(0)
	v_readfirstlane_b32 s6, v151
	s_cmp_eq_u32 s6, 8
	s_cbranch_scc0 .Lmg_flat
	s_barrier
	s_cmp_eq_u32 s10, 0
	s_cbranch_scc0 .Lmgx_wait
	s_mov_b64 s[6:7], exec
	s_mov_b64 exec, 1
	s_getreg_b32 s8, hwreg(HW_REG_XCC_ID, 0, 4)
	s_lshl_b32 s8, s8, 8
	s_lshl_b32 s9, s18, 11
	s_add_u32 s8, s8, s9
	s_add_u32 s8, s8, 0x1da5e000
	s_add_u32 s8, s96, s8
	s_addc_u32 s9, s97, 0
	v_mov_b32_e32 v147, 1
	v_mov_b32_e32 v149, 0
	global_atomic_add v151, v149, v147, s[8:9] sc0
	v_mov_b32_e32 v153, 0x125f0
	s_waitcnt vmcnt(0)
	ds_write_b32 v153, v151
	s_waitcnt lgkmcnt(0)
	s_mov_b64 exec, s[6:7]

; DI void phase_outproj(const Params& p, int l, char* smem, int tid) {
;     ...
;   for (int it = (dyn ? fetch_item(qc, smem) : (int)blockIdx.x); it < 272 * 8; it = (dyn ? fetch_item(qc, smem) : it + (int)gridDim.x)) {
.Lop_item:
	v_mov_b32_e32 v115, 0x12604
	ds_read_b32 v114, v115
	s_waitcnt lgkmcnt(0)
	v_readfirstlane_b32 s6, v114
	s_cmp_eq_u32 s6, 8
	s_cbranch_scc0 .Lop_flat
	s_barrier
	s_cmp_eq_u32 s10, 0
	s_cbranch_scc0 .Lopx_wait
	s_mov_b64 s[6:7], exec
	s_mov_b64 exec, 1
	s_getreg_b32 s8, hwreg(HW_REG_XCC_ID, 0, 4)
	s_lshl_b32 s8, s8, 8
	s_lshl_b32 s9, s18, 11
	s_add_u32 s8, s8, s9
	s_add_u32 s8, s8, 0x1da5f000
	s_add_u32 s8, s96, s8
	s_addc_u32 s9, s97, 0
	v_mov_b32_e32 v112, 1
	v_mov_b32_e32 v113, 0
	global_atomic_add v114, v113, v112, s[8:9] sc0
	v_mov_b32_e32 v115, 0x125f0
	s_waitcnt vmcnt(0)
	ds_write_b32 v115, v114
	s_waitcnt lgkmcnt(0)
	s_mov_b64 exec, s[6:7]
